# out-projection final epilogue no longer drains stores between row groups; in-proj epilogue stores as global instead of flat
# baseline (speedup 1.0000x reference)
.LBB0_232:
	v_cvt_f32_ubyte0_e32 v49, v118
	v_max_f32_e32 v49, 0x2f800000, v49
	s_waitcnt lgkmcnt(0)
	v_lshlrev_b32_e32 v48, 16, v58
	v_mul_f32_e32 v49, 0x3b808081, v49
	v_fmac_f32_e32 v48, v34, v49
	v_cvt_f32_ubyte1_e32 v49, v118
	v_max_f32_e32 v49, 0x2f800000, v49
	v_and_b32_e32 v34, 0xffff0000, v58
	v_mul_f32_e32 v49, 0x3b808081, v49
	v_fmac_f32_e32 v34, v35, v49
	v_cvt_f32_ubyte2_e32 v49, v118
	v_max_f32_e32 v49, 0x2f800000, v49
	v_lshlrev_b32_e32 v35, 16, v59
	v_mul_f32_e32 v49, 0x3b808081, v49
	v_fmac_f32_e32 v35, v36, v49
	v_cvt_f32_ubyte3_e32 v49, v118
	v_max_f32_e32 v49, 0x2f800000, v49
	v_and_b32_e32 v36, 0xffff0000, v59
	v_mul_f32_e32 v49, 0x3b808081, v49
	v_fmac_f32_e32 v36, v37, v49
	v_cvt_f32_ubyte0_e32 v49, v119
	v_max_f32_e32 v49, 0x2f800000, v49
	v_lshlrev_b32_e32 v37, 16, v60
	v_mul_f32_e32 v49, 0x3b808081, v49
	v_fmac_f32_e32 v37, v30, v49
	v_cvt_f32_ubyte1_e32 v30, v119
	v_max_f32_e32 v30, 0x2f800000, v30
	v_and_b32_e32 v49, 0xffff0000, v60
	v_mul_f32_e32 v30, 0x3b808081, v30
	v_fmac_f32_e32 v49, v31, v30
	v_cvt_f32_ubyte2_e32 v30, v119
	v_max_f32_e32 v30, 0x2f800000, v30
	v_lshlrev_b32_e32 v50, 16, v61
	v_mul_f32_e32 v30, 0x3b808081, v30
	v_fmac_f32_e32 v50, v32, v30
	v_cvt_f32_ubyte3_e32 v30, v119
	v_max_f32_e32 v30, 0x2f800000, v30
	v_and_b32_e32 v51, 0xffff0000, v61
	v_mul_f32_e32 v30, 0x3b808081, v30
	v_fmac_f32_e32 v51, v33, v30
	v_cvt_pk_bf16_f32 v30, v48, v34
	v_cvt_pk_bf16_f32 v31, v35, v36
	v_cvt_pk_bf16_f32 v32, v37, v49
	v_cvt_pk_bf16_f32 v33, v50, v51
	flat_store_dwordx4 v[62:63], v[30:33]
	s_and_b64 vcc, exec, s[38:39]
	s_mov_b32 s68, s66
	v_cvt_f32_ubyte0_e32 v31, v120
	v_max_f32_e32 v31, 0x2f800000, v31
	v_lshlrev_b32_e32 v30, 16, v54
	v_mul_f32_e32 v31, 0x3b808081, v31
	v_fmac_f32_e32 v30, v26, v31
	v_cvt_f32_ubyte1_e32 v31, v120
	v_max_f32_e32 v31, 0x2f800000, v31
	v_and_b32_e32 v26, 0xffff0000, v54
	v_mul_f32_e32 v31, 0x3b808081, v31
	v_fmac_f32_e32 v26, v27, v31
	v_cvt_f32_ubyte2_e32 v31, v120
	v_max_f32_e32 v31, 0x2f800000, v31
	v_lshlrev_b32_e32 v27, 16, v55
	v_mul_f32_e32 v31, 0x3b808081, v31
	v_fmac_f32_e32 v27, v28, v31
	v_cvt_f32_ubyte3_e32 v31, v120
	v_max_f32_e32 v31, 0x2f800000, v31
	v_and_b32_e32 v28, 0xffff0000, v55
	v_mul_f32_e32 v31, 0x3b808081, v31
	v_fmac_f32_e32 v28, v29, v31
	v_cvt_f32_ubyte0_e32 v31, v121
	v_max_f32_e32 v31, 0x2f800000, v31
	v_lshlrev_b32_e32 v29, 16, v56
	v_mul_f32_e32 v31, 0x3b808081, v31
	v_fmac_f32_e32 v29, v22, v31
	v_cvt_f32_ubyte1_e32 v22, v121
	v_max_f32_e32 v22, 0x2f800000, v22
	v_and_b32_e32 v31, 0xffff0000, v56
	v_mul_f32_e32 v22, 0x3b808081, v22
	v_fmac_f32_e32 v31, v23, v22
	v_cvt_f32_ubyte2_e32 v22, v121
	v_max_f32_e32 v22, 0x2f800000, v22
	v_lshlrev_b32_e32 v32, 16, v57
	v_mul_f32_e32 v22, 0x3b808081, v22
	v_fmac_f32_e32 v32, v24, v22
	v_cvt_f32_ubyte3_e32 v22, v121
	v_max_f32_e32 v22, 0x2f800000, v22
	v_and_b32_e32 v33, 0xffff0000, v57
	v_mul_f32_e32 v22, 0x3b808081, v22
	v_fmac_f32_e32 v33, v25, v22
	v_cvt_pk_bf16_f32 v22, v30, v26
	v_cvt_pk_bf16_f32 v23, v27, v28
	v_cvt_pk_bf16_f32 v24, v29, v31
	v_cvt_pk_bf16_f32 v25, v32, v33
	flat_store_dwordx4 v[62:63], v[22:25] offset:256
	s_mov_b32 s41, s64
	s_mov_b32 s67, s44
	v_cvt_f32_ubyte0_e32 v23, v106
	v_max_f32_e32 v23, 0x2f800000, v23
	v_lshlrev_b32_e32 v22, 16, v42
	v_mul_f32_e32 v23, 0x3b808081, v23
	v_fmac_f32_e32 v22, v18, v23
	v_cvt_f32_ubyte1_e32 v23, v106
	v_max_f32_e32 v23, 0x2f800000, v23
	v_and_b32_e32 v18, 0xffff0000, v42
	v_mul_f32_e32 v23, 0x3b808081, v23
	v_fmac_f32_e32 v18, v19, v23
	v_cvt_f32_ubyte2_e32 v23, v106
	v_max_f32_e32 v23, 0x2f800000, v23
	v_lshlrev_b32_e32 v19, 16, v43
	v_mul_f32_e32 v23, 0x3b808081, v23
	v_fmac_f32_e32 v19, v20, v23
	v_cvt_f32_ubyte3_e32 v23, v106
	v_max_f32_e32 v23, 0x2f800000, v23
	v_and_b32_e32 v20, 0xffff0000, v43
	v_mul_f32_e32 v23, 0x3b808081, v23
	v_fmac_f32_e32 v20, v21, v23
	v_cvt_f32_ubyte0_e32 v23, v107
	v_max_f32_e32 v23, 0x2f800000, v23
	v_lshlrev_b32_e32 v21, 16, v44
	v_mul_f32_e32 v23, 0x3b808081, v23
	v_fmac_f32_e32 v21, v8, v23
	v_cvt_f32_ubyte1_e32 v8, v107
	v_max_f32_e32 v8, 0x2f800000, v8
	v_and_b32_e32 v23, 0xffff0000, v44
	v_mul_f32_e32 v8, 0x3b808081, v8
	v_fmac_f32_e32 v23, v9, v8
	v_cvt_f32_ubyte2_e32 v8, v107
	v_max_f32_e32 v8, 0x2f800000, v8
	v_lshlrev_b32_e32 v24, 16, v45
	v_mul_f32_e32 v8, 0x3b808081, v8
	v_fmac_f32_e32 v24, v10, v8
	v_cvt_f32_ubyte3_e32 v8, v107
	v_max_f32_e32 v8, 0x2f800000, v8
	v_and_b32_e32 v25, 0xffff0000, v45
	v_mul_f32_e32 v8, 0x3b808081, v8
	v_fmac_f32_e32 v25, v11, v8
	v_cvt_pk_bf16_f32 v8, v22, v18
	v_cvt_pk_bf16_f32 v9, v19, v20
	v_cvt_pk_bf16_f32 v10, v21, v23
	v_cvt_pk_bf16_f32 v11, v24, v25
	flat_store_dwordx4 v[46:47], v[8:11]
	s_mov_b32 s40, s46
	s_mov_b64 s[54:55], s[50:51]
	v_cvt_f32_ubyte0_e32 v9, v108
	v_max_f32_e32 v9, 0x2f800000, v9
	v_lshlrev_b32_e32 v8, 16, v38
	v_mul_f32_e32 v9, 0x3b808081, v9
	v_fmac_f32_e32 v8, v4, v9
	v_cvt_f32_ubyte1_e32 v9, v108
	v_max_f32_e32 v9, 0x2f800000, v9
	v_and_b32_e32 v4, 0xffff0000, v38
	v_mul_f32_e32 v9, 0x3b808081, v9
	v_fmac_f32_e32 v4, v5, v9
	v_cvt_f32_ubyte2_e32 v9, v108
	v_max_f32_e32 v9, 0x2f800000, v9
	v_lshlrev_b32_e32 v5, 16, v39
	v_mul_f32_e32 v9, 0x3b808081, v9
	v_fmac_f32_e32 v5, v6, v9
	v_cvt_f32_ubyte3_e32 v9, v108
	v_max_f32_e32 v9, 0x2f800000, v9
	v_and_b32_e32 v6, 0xffff0000, v39
	v_mul_f32_e32 v9, 0x3b808081, v9
	v_fmac_f32_e32 v6, v7, v9
	v_cvt_f32_ubyte0_e32 v9, v109
	v_max_f32_e32 v9, 0x2f800000, v9
	v_lshlrev_b32_e32 v7, 16, v40
	v_mul_f32_e32 v9, 0x3b808081, v9
	v_fmac_f32_e32 v7, v0, v9
	v_cvt_f32_ubyte1_e32 v0, v109
	v_max_f32_e32 v0, 0x2f800000, v0
	v_and_b32_e32 v9, 0xffff0000, v40
	v_mul_f32_e32 v0, 0x3b808081, v0
	v_fmac_f32_e32 v9, v1, v0
	v_cvt_f32_ubyte2_e32 v0, v109
	v_max_f32_e32 v0, 0x2f800000, v0
	v_lshlrev_b32_e32 v10, 16, v41
	v_mul_f32_e32 v0, 0x3b808081, v0
	v_fmac_f32_e32 v10, v2, v0
	v_cvt_f32_ubyte3_e32 v0, v109
	v_max_f32_e32 v0, 0x2f800000, v0
	v_and_b32_e32 v11, 0xffff0000, v41
	v_mul_f32_e32 v0, 0x3b808081, v0
	s_mov_b64 s[52:53], s[48:49]
	v_fmac_f32_e32 v11, v3, v0
	v_cvt_pk_bf16_f32 v0, v8, v4
	v_cvt_pk_bf16_f32 v1, v5, v6
	v_cvt_pk_bf16_f32 v2, v7, v9
	v_cvt_pk_bf16_f32 v3, v10, v11
	flat_store_dwordx4 v[46:47], v[0:3] offset:256
	s_cbranch_vccnz .LBB0_270

.LBB0_254:
	v_cvt_f32_ubyte0_e32 v117, v154
	v_max_f32_e32 v117, 0x2f800000, v117
	s_waitcnt lgkmcnt(0)
	v_lshlrev_b32_e32 v116, 16, v130
	v_mul_f32_e32 v117, 0x3b808081, v117
	v_fmac_f32_e32 v116, v98, v117
	v_cvt_f32_ubyte1_e32 v117, v154
	v_max_f32_e32 v117, 0x2f800000, v117
	v_and_b32_e32 v98, 0xffff0000, v130
	v_mul_f32_e32 v117, 0x3b808081, v117
	v_fmac_f32_e32 v98, v99, v117
	v_cvt_f32_ubyte2_e32 v117, v154
	v_max_f32_e32 v117, 0x2f800000, v117
	v_lshlrev_b32_e32 v99, 16, v131
	v_mul_f32_e32 v117, 0x3b808081, v117
	v_fmac_f32_e32 v99, v100, v117
	v_cvt_f32_ubyte3_e32 v117, v154
	v_max_f32_e32 v117, 0x2f800000, v117
	v_and_b32_e32 v100, 0xffff0000, v131
	v_mul_f32_e32 v117, 0x3b808081, v117
	v_fmac_f32_e32 v100, v101, v117
	v_cvt_f32_ubyte0_e32 v117, v155
	v_max_f32_e32 v117, 0x2f800000, v117
	v_lshlrev_b32_e32 v101, 16, v132
	v_mul_f32_e32 v117, 0x3b808081, v117
	v_fmac_f32_e32 v101, v94, v117
	v_cvt_f32_ubyte1_e32 v94, v155
	v_max_f32_e32 v94, 0x2f800000, v94
	v_and_b32_e32 v117, 0xffff0000, v132
	v_mul_f32_e32 v94, 0x3b808081, v94
	v_fmac_f32_e32 v117, v95, v94
	v_cvt_f32_ubyte2_e32 v94, v155
	v_max_f32_e32 v94, 0x2f800000, v94
	v_lshlrev_b32_e32 v122, 16, v133
	v_mul_f32_e32 v94, 0x3b808081, v94
	v_fmac_f32_e32 v122, v96, v94
	v_cvt_f32_ubyte3_e32 v94, v155
	v_max_f32_e32 v94, 0x2f800000, v94
	v_and_b32_e32 v123, 0xffff0000, v133
	v_mul_f32_e32 v94, 0x3b808081, v94
	v_fmac_f32_e32 v123, v97, v94
	v_cvt_pk_bf16_f32 v94, v116, v98
	v_cvt_pk_bf16_f32 v95, v99, v100
	v_cvt_pk_bf16_f32 v96, v101, v117
	v_cvt_pk_bf16_f32 v97, v122, v123
	flat_store_dwordx4 v[138:139], v[94:97]
	v_ashrrev_i32_e32 v215, 31, v214
	s_and_b64 vcc, exec, s[40:41]
	v_cvt_f32_ubyte0_e32 v95, v156
	v_max_f32_e32 v95, 0x2f800000, v95
	v_lshlrev_b32_e32 v94, 16, v126
	v_mul_f32_e32 v95, 0x3b808081, v95
	v_fmac_f32_e32 v94, v90, v95
	v_cvt_f32_ubyte1_e32 v95, v156
	v_max_f32_e32 v95, 0x2f800000, v95
	v_and_b32_e32 v90, 0xffff0000, v126
	v_mul_f32_e32 v95, 0x3b808081, v95
	v_fmac_f32_e32 v90, v91, v95
	v_cvt_f32_ubyte2_e32 v95, v156
	v_max_f32_e32 v95, 0x2f800000, v95
	v_lshlrev_b32_e32 v91, 16, v127
	v_mul_f32_e32 v95, 0x3b808081, v95
	v_fmac_f32_e32 v91, v92, v95
	v_cvt_f32_ubyte3_e32 v95, v156
	v_max_f32_e32 v95, 0x2f800000, v95
	v_and_b32_e32 v92, 0xffff0000, v127
	v_mul_f32_e32 v95, 0x3b808081, v95
	v_fmac_f32_e32 v92, v93, v95
	v_cvt_f32_ubyte0_e32 v95, v157
	v_max_f32_e32 v95, 0x2f800000, v95
	v_lshlrev_b32_e32 v93, 16, v128
	v_mul_f32_e32 v95, 0x3b808081, v95
	v_fmac_f32_e32 v93, v86, v95
	v_cvt_f32_ubyte1_e32 v86, v157
	v_max_f32_e32 v86, 0x2f800000, v86
	v_and_b32_e32 v95, 0xffff0000, v128
	v_mul_f32_e32 v86, 0x3b808081, v86
	v_fmac_f32_e32 v95, v87, v86
	v_cvt_f32_ubyte2_e32 v86, v157
	v_max_f32_e32 v86, 0x2f800000, v86
	v_lshlrev_b32_e32 v96, 16, v129
	v_mul_f32_e32 v86, 0x3b808081, v86
	v_fmac_f32_e32 v96, v88, v86
	v_cvt_f32_ubyte3_e32 v86, v157
	v_max_f32_e32 v86, 0x2f800000, v86
	v_and_b32_e32 v97, 0xffff0000, v129
	v_mul_f32_e32 v86, 0x3b808081, v86
	v_fmac_f32_e32 v97, v89, v86
	v_cvt_pk_bf16_f32 v86, v94, v90
	v_cvt_pk_bf16_f32 v87, v91, v92
	v_cvt_pk_bf16_f32 v88, v93, v95
	v_cvt_pk_bf16_f32 v89, v96, v97
	flat_store_dwordx4 v[138:139], v[86:89] offset:256
	v_mov_b32_e32 v90, 0
	v_mov_b32_e32 v91, 0
	v_lshlrev_b64 v[86:87], 12, v[214:215]
	v_lshl_add_u64 v[86:87], s[0:1], 0, v[86:87]
	v_lshl_add_u64 v[94:95], v[208:209], 1, v[86:87]
	v_mov_b32_e32 v86, 0
	v_mov_b32_e32 v92, 0
	v_mov_b32_e32 v93, 0
	s_cbranch_vccnz .LBB0_256
	flat_load_dwordx4 v[90:93], v[94:95]

.LBB0_262:
	v_cvt_f32_ubyte0_e32 v81, v146
	v_max_f32_e32 v81, 0x2f800000, v81
	s_waitcnt lgkmcnt(0)
	v_lshlrev_b32_e32 v80, 16, v90
	v_mul_f32_e32 v81, 0x3b808081, v81
	v_fmac_f32_e32 v80, v66, v81
	v_cvt_f32_ubyte1_e32 v81, v146
	v_max_f32_e32 v81, 0x2f800000, v81
	v_and_b32_e32 v66, 0xffff0000, v90
	v_mul_f32_e32 v81, 0x3b808081, v81
	v_fmac_f32_e32 v66, v67, v81
	v_cvt_f32_ubyte2_e32 v81, v146
	v_max_f32_e32 v81, 0x2f800000, v81
	v_lshlrev_b32_e32 v67, 16, v91
	v_mul_f32_e32 v81, 0x3b808081, v81
	v_fmac_f32_e32 v67, v68, v81
	v_cvt_f32_ubyte3_e32 v81, v146
	v_max_f32_e32 v81, 0x2f800000, v81
	v_and_b32_e32 v68, 0xffff0000, v91
	v_mul_f32_e32 v81, 0x3b808081, v81
	v_fmac_f32_e32 v68, v69, v81
	v_cvt_f32_ubyte0_e32 v81, v147
	v_max_f32_e32 v81, 0x2f800000, v81
	v_lshlrev_b32_e32 v69, 16, v92
	v_mul_f32_e32 v81, 0x3b808081, v81
	v_fmac_f32_e32 v69, v62, v81
	v_cvt_f32_ubyte1_e32 v62, v147
	v_max_f32_e32 v62, 0x2f800000, v62
	v_and_b32_e32 v81, 0xffff0000, v92
	v_mul_f32_e32 v62, 0x3b808081, v62
	v_fmac_f32_e32 v81, v63, v62
	v_cvt_f32_ubyte2_e32 v62, v147
	v_max_f32_e32 v62, 0x2f800000, v62
	v_lshlrev_b32_e32 v82, 16, v93
	v_mul_f32_e32 v62, 0x3b808081, v62
	v_fmac_f32_e32 v82, v64, v62
	v_cvt_f32_ubyte3_e32 v62, v147
	v_max_f32_e32 v62, 0x2f800000, v62
	v_and_b32_e32 v83, 0xffff0000, v93
	v_mul_f32_e32 v62, 0x3b808081, v62
	v_fmac_f32_e32 v83, v65, v62
	v_cvt_pk_bf16_f32 v62, v80, v66
	v_cvt_pk_bf16_f32 v63, v67, v68
	v_cvt_pk_bf16_f32 v64, v69, v81
	v_cvt_pk_bf16_f32 v65, v82, v83
	flat_store_dwordx4 v[94:95], v[62:65]
	v_ashrrev_i32_e32 v211, 31, v210
	s_and_b64 vcc, exec, s[40:41]
	v_cvt_f32_ubyte0_e32 v63, v148
	v_max_f32_e32 v63, 0x2f800000, v63
	v_lshlrev_b32_e32 v62, 16, v86
	v_mul_f32_e32 v63, 0x3b808081, v63
	v_fmac_f32_e32 v62, v58, v63
	v_cvt_f32_ubyte1_e32 v63, v148
	v_max_f32_e32 v63, 0x2f800000, v63
	v_and_b32_e32 v58, 0xffff0000, v86
	v_mul_f32_e32 v63, 0x3b808081, v63
	v_fmac_f32_e32 v58, v59, v63
	v_cvt_f32_ubyte2_e32 v63, v148
	v_max_f32_e32 v63, 0x2f800000, v63
	v_lshlrev_b32_e32 v59, 16, v87
	v_mul_f32_e32 v63, 0x3b808081, v63
	v_fmac_f32_e32 v59, v60, v63
	v_cvt_f32_ubyte3_e32 v63, v148
	v_max_f32_e32 v63, 0x2f800000, v63
	v_and_b32_e32 v60, 0xffff0000, v87
	v_mul_f32_e32 v63, 0x3b808081, v63
	v_fmac_f32_e32 v60, v61, v63
	v_cvt_f32_ubyte0_e32 v63, v149
	v_max_f32_e32 v63, 0x2f800000, v63
	v_lshlrev_b32_e32 v61, 16, v88
	v_mul_f32_e32 v63, 0x3b808081, v63
	v_fmac_f32_e32 v61, v54, v63
	v_cvt_f32_ubyte1_e32 v54, v149
	v_max_f32_e32 v54, 0x2f800000, v54
	v_and_b32_e32 v63, 0xffff0000, v88
	v_mul_f32_e32 v54, 0x3b808081, v54
	v_fmac_f32_e32 v63, v55, v54
	v_cvt_f32_ubyte2_e32 v54, v149
	v_max_f32_e32 v54, 0x2f800000, v54
	v_lshlrev_b32_e32 v64, 16, v89
	v_mul_f32_e32 v54, 0x3b808081, v54
	v_fmac_f32_e32 v64, v56, v54
	v_cvt_f32_ubyte3_e32 v54, v149
	v_max_f32_e32 v54, 0x2f800000, v54
	v_and_b32_e32 v65, 0xffff0000, v89
	v_mul_f32_e32 v54, 0x3b808081, v54
	v_fmac_f32_e32 v65, v57, v54
	v_cvt_pk_bf16_f32 v54, v62, v58
	v_cvt_pk_bf16_f32 v55, v59, v60
	v_cvt_pk_bf16_f32 v56, v61, v63
	v_cvt_pk_bf16_f32 v57, v64, v65
	flat_store_dwordx4 v[94:95], v[54:57] offset:256
	v_mov_b32_e32 v58, 0
	v_mov_b32_e32 v59, 0
	v_lshlrev_b64 v[54:55], 12, v[210:211]
	v_lshl_add_u64 v[54:55], s[0:1], 0, v[54:55]
	v_lshl_add_u64 v[62:63], v[208:209], 1, v[54:55]
	v_mov_b32_e32 v54, 0
	v_mov_b32_e32 v60, 0
	v_mov_b32_e32 v61, 0
	s_cbranch_vccnz .LBB0_264
	flat_load_dwordx4 v[58:61], v[62:63]

.LBB0_1234:
	v_cvt_pk_bf16_f32 v160, v130, v131
	v_cvt_pk_bf16_f32 v161, v132, v133
	v_cvt_pk_bf16_f32 v162, v126, v127
	v_cvt_pk_bf16_f32 v163, v128, v129
	global_store_dwordx4 v[152:153], v[160:163], off
	v_cndmask_b32_e64 v152, 0, 1, s[46:47]
	v_cmp_ne_u32_e64 s[40:41], 1, v152
	s_andn2_b64 vcc, exec, s[46:47]
	s_mov_b64 s[46:47], -1
	s_cbranch_vccnz .LBB0_1236
	v_lshl_add_u64 v[150:151], v[182:183], 1, v[150:151]
	s_mov_b64 s[8:9], 0x100
	v_lshl_add_u64 v[152:153], v[150:151], 0, s[8:9]
	s_mov_b64 s[46:47], 0

.LBB0_1238:
	v_cvt_pk_bf16_f32 v162, v122, v123
	v_cvt_pk_bf16_f32 v163, v124, v125
	v_cvt_pk_bf16_f32 v164, v118, v119
	v_cvt_pk_bf16_f32 v165, v120, v121
	global_store_dwordx4 v[152:153], v[162:165], off
	v_or_b32_e32 v152, 16, v158
	v_mad_i64_i32 v[150:151], s[46:47], v152, s4, 0
	s_mov_b64 s[46:47], -1
	s_and_b64 vcc, exec, s[40:41]
	v_lshl_add_u64 v[150:151], s[0:1], 0, v[150:151]
	s_cbranch_vccnz .LBB0_1240
	v_lshl_add_u64 v[154:155], v[182:183], 1, v[150:151]
	s_mov_b64 s[46:47], 0

.LBB0_1242:
	s_and_b64 vcc, exec, s[40:41]
	s_mov_b64 s[46:47], -1
	v_cvt_pk_bf16_f32 v162, v114, v115
	v_cvt_pk_bf16_f32 v163, v116, v117
	v_cvt_pk_bf16_f32 v164, v110, v111
	v_cvt_pk_bf16_f32 v165, v112, v113
	global_store_dwordx4 v[154:155], v[162:165], off
	s_cbranch_vccnz .LBB0_1244
	v_lshl_add_u64 v[150:151], v[182:183], 1, v[150:151]
	s_mov_b64 s[8:9], 0x100
	v_lshl_add_u64 v[154:155], v[150:151], 0, s[8:9]
	s_mov_b64 s[46:47], 0

.LBB0_1246:
	v_cvt_pk_bf16_f32 v150, v106, v107
	v_cvt_pk_bf16_f32 v151, v108, v109
	v_cvt_pk_bf16_f32 v152, v102, v103
	v_cvt_pk_bf16_f32 v153, v104, v105
	global_store_dwordx4 v[154:155], v[150:153], off
	s_and_b64 vcc, exec, s[40:41]
	s_nop 0
	v_or_b32_e32 v152, 32, v158
	v_mad_i64_i32 v[150:151], s[46:47], v152, s4, 0
	s_mov_b64 s[46:47], -1
	v_lshl_add_u64 v[150:151], s[0:1], 0, v[150:151]
	s_cbranch_vccnz .LBB0_1248
	v_lshl_add_u64 v[154:155], v[182:183], 1, v[150:151]
	s_mov_b64 s[46:47], 0

.LBB0_1250:
	s_and_b64 vcc, exec, s[40:41]
	s_mov_b64 s[46:47], -1
	v_cvt_pk_bf16_f32 v162, v98, v99
	v_cvt_pk_bf16_f32 v163, v100, v101
	v_cvt_pk_bf16_f32 v164, v94, v95
	v_cvt_pk_bf16_f32 v165, v96, v97
	global_store_dwordx4 v[154:155], v[162:165], off
	s_cbranch_vccnz .LBB0_1252
	v_lshl_add_u64 v[150:151], v[182:183], 1, v[150:151]
	s_mov_b64 s[8:9], 0x100
	v_lshl_add_u64 v[154:155], v[150:151], 0, s[8:9]
	s_mov_b64 s[46:47], 0

.LBB0_1254:
	v_cvt_pk_bf16_f32 v150, v90, v91
	v_cvt_pk_bf16_f32 v151, v92, v93
	v_cvt_pk_bf16_f32 v152, v86, v87
	v_cvt_pk_bf16_f32 v153, v88, v89
	global_store_dwordx4 v[154:155], v[150:153], off
	s_and_b64 vcc, exec, s[40:41]
	s_nop 0
	v_or_b32_e32 v152, 48, v158
	v_mad_i64_i32 v[150:151], s[46:47], v152, s4, 0
	s_mov_b64 s[46:47], -1
	v_lshl_add_u64 v[150:151], s[0:1], 0, v[150:151]
	s_cbranch_vccnz .LBB0_1256
	v_lshl_add_u64 v[154:155], v[182:183], 1, v[150:151]
	s_mov_b64 s[46:47], 0

.LBB0_1258:
	s_and_b64 vcc, exec, s[40:41]
	s_mov_b64 s[46:47], -1
	v_cvt_pk_bf16_f32 v162, v82, v83
	v_cvt_pk_bf16_f32 v163, v84, v85
	v_cvt_pk_bf16_f32 v164, v78, v79
	v_cvt_pk_bf16_f32 v165, v80, v81
	global_store_dwordx4 v[154:155], v[162:165], off
	s_cbranch_vccnz .LBB0_1260
	v_lshl_add_u64 v[150:151], v[182:183], 1, v[150:151]
	s_mov_b64 s[8:9], 0x100
	v_lshl_add_u64 v[154:155], v[150:151], 0, s[8:9]
	s_mov_b64 s[46:47], 0

.LBB0_1262:
	v_cvt_pk_bf16_f32 v150, v74, v75
	v_cvt_pk_bf16_f32 v151, v76, v77
	v_cvt_pk_bf16_f32 v152, v70, v71
	v_cvt_pk_bf16_f32 v153, v72, v73
	global_store_dwordx4 v[154:155], v[150:153], off
	s_and_b64 vcc, exec, s[40:41]
	s_nop 0
	v_add_u32_e32 v152, 0x80, v158
	v_mad_i64_i32 v[150:151], s[46:47], v152, s4, 0
	s_mov_b64 s[46:47], -1
	v_lshl_add_u64 v[150:151], s[0:1], 0, v[150:151]
	s_cbranch_vccnz .LBB0_1264
	v_lshl_add_u64 v[154:155], v[182:183], 1, v[150:151]
	s_mov_b64 s[46:47], 0

.LBB0_1266:
	s_and_b64 vcc, exec, s[40:41]
	s_mov_b64 s[46:47], -1
	v_cvt_pk_bf16_f32 v162, v66, v67
	v_cvt_pk_bf16_f32 v163, v68, v69
	v_cvt_pk_bf16_f32 v164, v62, v63
	v_cvt_pk_bf16_f32 v165, v64, v65
	global_store_dwordx4 v[154:155], v[162:165], off
	s_cbranch_vccnz .LBB0_1268
	v_lshl_add_u64 v[150:151], v[182:183], 1, v[150:151]
	s_mov_b64 s[8:9], 0x100
	v_lshl_add_u64 v[154:155], v[150:151], 0, s[8:9]
	s_mov_b64 s[46:47], 0

.LBB0_1270:
	v_cvt_pk_bf16_f32 v150, v58, v59
	v_cvt_pk_bf16_f32 v151, v60, v61
	v_cvt_pk_bf16_f32 v152, v54, v55
	v_cvt_pk_bf16_f32 v153, v56, v57
	global_store_dwordx4 v[154:155], v[150:153], off
	s_and_b64 vcc, exec, s[40:41]
	s_nop 0
	v_add_u32_e32 v152, 0x90, v158
	v_mad_i64_i32 v[150:151], s[46:47], v152, s4, 0
	s_mov_b64 s[46:47], -1
	v_lshl_add_u64 v[150:151], s[0:1], 0, v[150:151]
	s_cbranch_vccnz .LBB0_1272
	v_lshl_add_u64 v[154:155], v[182:183], 1, v[150:151]
	s_mov_b64 s[46:47], 0

.LBB0_1274:
	s_and_b64 vcc, exec, s[40:41]
	s_mov_b64 s[46:47], -1
	v_cvt_pk_bf16_f32 v162, v50, v51
	v_cvt_pk_bf16_f32 v163, v52, v53
	v_cvt_pk_bf16_f32 v164, v46, v47
	v_cvt_pk_bf16_f32 v165, v48, v49
	global_store_dwordx4 v[154:155], v[162:165], off
	s_cbranch_vccnz .LBB0_1276
	v_lshl_add_u64 v[150:151], v[182:183], 1, v[150:151]
	s_mov_b64 s[8:9], 0x100
	v_lshl_add_u64 v[154:155], v[150:151], 0, s[8:9]
	s_mov_b64 s[46:47], 0

.LBB0_1278:
	v_cvt_pk_bf16_f32 v150, v42, v43
	v_cvt_pk_bf16_f32 v151, v44, v45
	v_cvt_pk_bf16_f32 v152, v38, v39
	v_cvt_pk_bf16_f32 v153, v40, v41
	global_store_dwordx4 v[154:155], v[150:153], off
	s_and_b64 vcc, exec, s[40:41]
	s_nop 0
	v_add_u32_e32 v152, 0xa0, v158
	v_mad_i64_i32 v[150:151], s[46:47], v152, s4, 0
	s_mov_b64 s[46:47], -1
	v_lshl_add_u64 v[150:151], s[0:1], 0, v[150:151]
	s_cbranch_vccnz .LBB0_1280
	v_lshl_add_u64 v[154:155], v[182:183], 1, v[150:151]
	s_mov_b64 s[46:47], 0

.LBB0_1282:
	s_and_b64 vcc, exec, s[40:41]
	s_mov_b64 s[46:47], -1
	v_cvt_pk_bf16_f32 v162, v34, v35
	v_cvt_pk_bf16_f32 v163, v36, v37
	v_cvt_pk_bf16_f32 v164, v30, v31
	v_cvt_pk_bf16_f32 v165, v32, v33
	global_store_dwordx4 v[154:155], v[162:165], off
	s_cbranch_vccnz .LBB0_1284
	v_lshl_add_u64 v[150:151], v[182:183], 1, v[150:151]
	s_mov_b64 s[8:9], 0x100
	v_lshl_add_u64 v[154:155], v[150:151], 0, s[8:9]
	s_mov_b64 s[46:47], 0

.LBB0_1286:
	v_cvt_pk_bf16_f32 v150, v26, v27
	v_cvt_pk_bf16_f32 v151, v28, v29
	v_cvt_pk_bf16_f32 v152, v22, v23
	v_cvt_pk_bf16_f32 v153, v24, v25
	global_store_dwordx4 v[154:155], v[150:153], off
	s_and_b64 vcc, exec, s[40:41]
	s_nop 0
	v_add_u32_e32 v152, 0xb0, v158
	v_mad_i64_i32 v[150:151], s[46:47], v152, s4, 0
	s_mov_b64 s[46:47], -1
	v_lshl_add_u64 v[150:151], s[0:1], 0, v[150:151]
	s_cbranch_vccnz .LBB0_1288
	v_lshl_add_u64 v[154:155], v[182:183], 1, v[150:151]
	s_mov_b64 s[46:47], 0

.LBB0_1290:
	s_and_b64 vcc, exec, s[40:41]
	s_mov_b64 s[40:41], -1
	v_cvt_pk_bf16_f32 v162, v18, v19
	v_cvt_pk_bf16_f32 v163, v20, v21
	v_cvt_pk_bf16_f32 v164, v8, v9
	v_cvt_pk_bf16_f32 v165, v10, v11
	global_store_dwordx4 v[154:155], v[162:165], off
	s_cbranch_vccnz .LBB0_1292
	v_lshl_add_u64 v[150:151], v[182:183], 1, v[150:151]
	s_mov_b64 s[8:9], 0x100
	v_lshl_add_u64 v[154:155], v[150:151], 0, s[8:9]
	s_mov_b64 s[40:41], 0

; __device__ __forceinline__ unsigned q8(float x) { return (unsigned)__float2uint_rn(__builtin_amdgcn_rcpf(fmaf(__expf(-x), 1.0f / 255.0f, 1.0f / 255.0f))); }
; __device__ __forceinline__ unsigned q8x4(const f32x4 v) { return q8(v[0]) | (q8(v[1]) << 8) | (q8(v[2]) << 16) | (q8(v[3]) << 24); }
.LBB0_1294:
	s_mov_b64 s[40:41], 0
	v_cvt_pk_bf16_f32 v150, v4, v5
	v_cvt_pk_bf16_f32 v151, v6, v7
	v_cvt_pk_bf16_f32 v152, v0, v1
	v_cvt_pk_bf16_f32 v153, v2, v3
	global_store_dwordx4 v[154:155], v[150:153], off
.LBB0_1295:
	s_and_b64 vcc, exec, s[40:41]
	s_cbranch_vccz .LBB0_1220
	v_mul_f32_e32 v130, 0xbfb8aa3b, v130
	v_mul_f32_e32 v131, 0xbfb8aa3b, v131
	v_exp_f32_e32 v130, v130
	v_exp_f32_e32 v131, v131
	v_mul_f32_e32 v132, 0xbfb8aa3b, v132
	v_mul_f32_e32 v133, 0xbfb8aa3b, v133
	v_fmamk_f32 v130, v130, 0x3b808081, v227
	v_fmamk_f32 v131, v131, 0x3b808081, v227
	v_rcp_f32_e32 v130, v130
	v_rcp_f32_e32 v131, v131
	v_exp_f32_e32 v132, v132
	v_exp_f32_e32 v133, v133
	v_mul_f32_e32 v114, 0xbfb8aa3b, v114
	v_mul_f32_e32 v115, 0xbfb8aa3b, v115
	v_exp_f32_e32 v114, v114
	v_exp_f32_e32 v115, v115
	v_mul_f32_e32 v126, 0xbfb8aa3b, v126
	v_rndne_f32_e32 v130, v130
	v_rndne_f32_e32 v131, v131
	v_fmamk_f32 v132, v132, 0x3b808081, v227
	v_fmamk_f32 v133, v133, 0x3b808081, v227
	v_exp_f32_e32 v126, v126
	v_mul_f32_e32 v127, 0xbfb8aa3b, v127
	v_mul_f32_e32 v118, 0xbfb8aa3b, v118
	v_mul_f32_e32 v119, 0xbfb8aa3b, v119
	v_cvt_u32_f32_e32 v130, v130
	v_cvt_u32_f32_e32 v131, v131
	v_rcp_f32_e32 v132, v132
	v_rcp_f32_e32 v133, v133
	v_exp_f32_e32 v127, v127
	v_mul_f32_e32 v128, 0xbfb8aa3b, v128
	v_mul_f32_e32 v129, 0xbfb8aa3b, v129
	v_exp_f32_e32 v118, v118
	v_exp_f32_e32 v119, v119
	v_mul_f32_e32 v120, 0xbfb8aa3b, v120
	v_mul_f32_e32 v121, 0xbfb8aa3b, v121
	v_exp_f32_e32 v128, v128
	v_exp_f32_e32 v129, v129
	v_exp_f32_e32 v120, v120
	v_exp_f32_e32 v121, v121
	v_fmamk_f32 v114, v114, 0x3b808081, v227
	v_fmamk_f32 v115, v115, 0x3b808081, v227
	v_mul_f32_e32 v116, 0xbfb8aa3b, v116
	v_mul_f32_e32 v117, 0xbfb8aa3b, v117
	v_rcp_f32_e32 v114, v114
	v_rcp_f32_e32 v115, v115
	v_exp_f32_e32 v116, v116
	v_exp_f32_e32 v117, v117
	v_mul_f32_e32 v98, 0xbfb8aa3b, v98
	v_mul_f32_e32 v99, 0xbfb8aa3b, v99
	v_fmamk_f32 v126, v126, 0x3b808081, v227
	v_exp_f32_e32 v98, v98
	v_exp_f32_e32 v99, v99
	v_lshl_or_b32 v130, v131, 8, v130
	v_rndne_f32_e32 v131, v132
	v_rndne_f32_e32 v132, v133
	v_rcp_f32_e32 v133, v126
	v_fmamk_f32 v126, v127, 0x3b808081, v227
	v_mul_f32_e32 v122, 0xbfb8aa3b, v122
	v_mul_f32_e32 v123, 0xbfb8aa3b, v123
	v_fmamk_f32 v118, v118, 0x3b808081, v227
	v_fmamk_f32 v119, v119, 0x3b808081, v227
	v_cvt_u32_f32_sdwa v131, v131 dst_sel:WORD_1 dst_unused:UNUSED_PAD src0_sel:DWORD
	v_cvt_u32_f32_sdwa v132, v132 dst_sel:BYTE_3 dst_unused:UNUSED_PAD src0_sel:DWORD
	v_rcp_f32_e32 v127, v126
	v_fmamk_f32 v128, v128, 0x3b808081, v227
	v_fmamk_f32 v129, v129, 0x3b808081, v227
	v_exp_f32_e32 v122, v122
	v_exp_f32_e32 v123, v123
	v_mul_f32_e32 v124, 0xbfb8aa3b, v124
	v_mul_f32_e32 v125, 0xbfb8aa3b, v125
	v_rcp_f32_e32 v118, v118
	v_rcp_f32_e32 v119, v119
	v_fmamk_f32 v120, v120, 0x3b808081, v227
	v_fmamk_f32 v121, v121, 0x3b808081, v227
	v_mul_f32_e32 v110, 0xbfb8aa3b, v110
	v_rcp_f32_e32 v128, v128
	v_rcp_f32_e32 v129, v129
	v_exp_f32_e32 v124, v124
	v_exp_f32_e32 v125, v125
	v_rcp_f32_e32 v120, v120
	v_rcp_f32_e32 v121, v121
	v_rndne_f32_e32 v114, v114
	v_rndne_f32_e32 v115, v115
	v_fmamk_f32 v116, v116, 0x3b808081, v227
	v_fmamk_f32 v117, v117, 0x3b808081, v227
	v_exp_f32_e32 v110, v110
	v_mul_f32_e32 v111, 0xbfb8aa3b, v111
	v_mul_f32_e32 v102, 0xbfb8aa3b, v102
	v_mul_f32_e32 v103, 0xbfb8aa3b, v103
	v_cvt_u32_f32_e32 v114, v114
	v_cvt_u32_f32_e32 v115, v115
	v_rcp_f32_e32 v116, v116
	v_rcp_f32_e32 v117, v117
	v_exp_f32_e32 v111, v111
	v_mul_f32_e32 v112, 0xbfb8aa3b, v112
	v_mul_f32_e32 v113, 0xbfb8aa3b, v113
	v_exp_f32_e32 v102, v102
	v_exp_f32_e32 v103, v103
	v_mul_f32_e32 v104, 0xbfb8aa3b, v104
	v_mul_f32_e32 v105, 0xbfb8aa3b, v105
	v_fmamk_f32 v98, v98, 0x3b808081, v227
	v_fmamk_f32 v99, v99, 0x3b808081, v227
	v_mul_f32_e32 v100, 0xbfb8aa3b, v100
	v_mul_f32_e32 v101, 0xbfb8aa3b, v101
	v_exp_f32_e32 v112, v112
	v_exp_f32_e32 v113, v113
	v_exp_f32_e32 v104, v104
	v_exp_f32_e32 v105, v105
	v_rcp_f32_e32 v98, v98
	v_rcp_f32_e32 v99, v99
	v_exp_f32_e32 v100, v100
	v_exp_f32_e32 v101, v101
	v_mul_f32_e32 v82, 0xbfb8aa3b, v82
	v_mul_f32_e32 v83, 0xbfb8aa3b, v83
	v_or3_b32 v126, v130, v131, v132
	v_rndne_f32_e32 v130, v133
	v_rndne_f32_e32 v127, v127
	v_fmamk_f32 v122, v122, 0x3b808081, v227
	v_fmamk_f32 v123, v123, 0x3b808081, v227
	v_rndne_f32_e32 v118, v118
	v_rndne_f32_e32 v119, v119
	v_exp_f32_e32 v82, v82
	v_exp_f32_e32 v83, v83
	v_cvt_u32_f32_e32 v130, v130
	v_cvt_u32_f32_e32 v127, v127
	v_rndne_f32_e32 v128, v128
	v_rndne_f32_e32 v129, v129
	v_rcp_f32_e32 v122, v122
	v_rcp_f32_e32 v123, v123
	v_fmamk_f32 v124, v124, 0x3b808081, v227
	v_fmamk_f32 v125, v125, 0x3b808081, v227
	v_cvt_u32_f32_e32 v118, v118
	v_cvt_u32_f32_e32 v119, v119
	v_rndne_f32_e32 v120, v120
	v_rndne_f32_e32 v121, v121
	v_fmamk_f32 v110, v110, 0x3b808081, v227
	v_mul_f32_e32 v106, 0xbfb8aa3b, v106
	v_mul_f32_e32 v107, 0xbfb8aa3b, v107
	v_cvt_u32_f32_sdwa v128, v128 dst_sel:WORD_1 dst_unused:UNUSED_PAD src0_sel:DWORD
	v_cvt_u32_f32_sdwa v129, v129 dst_sel:BYTE_3 dst_unused:UNUSED_PAD src0_sel:DWORD
	v_rcp_f32_e32 v124, v124
	v_rcp_f32_e32 v125, v125
	v_cvt_u32_f32_sdwa v120, v120 dst_sel:WORD_1 dst_unused:UNUSED_PAD src0_sel:DWORD
	v_cvt_u32_f32_sdwa v121, v121 dst_sel:BYTE_3 dst_unused:UNUSED_PAD src0_sel:DWORD
	v_lshl_or_b32 v114, v115, 8, v114
	v_rndne_f32_e32 v115, v116
	v_rndne_f32_e32 v116, v117
	v_rcp_f32_e32 v117, v110
	v_fmamk_f32 v110, v111, 0x3b808081, v227
	v_exp_f32_e32 v106, v106
	v_exp_f32_e32 v107, v107
	v_mul_f32_e32 v108, 0xbfb8aa3b, v108
	v_mul_f32_e32 v109, 0xbfb8aa3b, v109
	v_fmamk_f32 v102, v102, 0x3b808081, v227
	v_fmamk_f32 v103, v103, 0x3b808081, v227
	v_mul_f32_e32 v94, 0xbfb8aa3b, v94
; __device__ __forceinline__ unsigned q8(float x) { return (unsigned)__float2uint_rn(__builtin_amdgcn_rcpf(fmaf(__expf(-x), 1.0f / 255.0f, 1.0f / 255.0f))); }
; __device__ __forceinline__ unsigned q8x4(const f32x4 v) { return q8(v[0]) | (q8(v[1]) << 8) | (q8(v[2]) << 16) | (q8(v[3]) << 24); }
	v_cvt_u32_f32_sdwa v115, v115 dst_sel:WORD_1 dst_unused:UNUSED_PAD src0_sel:DWORD
	v_cvt_u32_f32_sdwa v116, v116 dst_sel:BYTE_3 dst_unused:UNUSED_PAD src0_sel:DWORD
	v_rcp_f32_e32 v111, v110
	v_fmamk_f32 v112, v112, 0x3b808081, v227
	v_fmamk_f32 v113, v113, 0x3b808081, v227
	v_exp_f32_e32 v108, v108
	v_exp_f32_e32 v109, v109
	v_rcp_f32_e32 v102, v102
	v_rcp_f32_e32 v103, v103
	v_fmamk_f32 v104, v104, 0x3b808081, v227
	v_fmamk_f32 v105, v105, 0x3b808081, v227
	v_rndne_f32_e32 v98, v98
	v_rndne_f32_e32 v99, v99
	v_fmamk_f32 v100, v100, 0x3b808081, v227
	v_fmamk_f32 v101, v101, 0x3b808081, v227
	v_exp_f32_e32 v94, v94
	v_mul_f32_e32 v95, 0xbfb8aa3b, v95
	v_mul_f32_e32 v86, 0xbfb8aa3b, v86
	v_mul_f32_e32 v87, 0xbfb8aa3b, v87
	v_rcp_f32_e32 v112, v112
	v_rcp_f32_e32 v113, v113
	v_rcp_f32_e32 v104, v104
	v_rcp_f32_e32 v105, v105
	v_cvt_u32_f32_e32 v98, v98
	v_cvt_u32_f32_e32 v99, v99
	v_rcp_f32_e32 v100, v100
	v_rcp_f32_e32 v101, v101
	v_exp_f32_e32 v95, v95
	v_mul_f32_e32 v96, 0xbfb8aa3b, v96
	v_mul_f32_e32 v97, 0xbfb8aa3b, v97
	v_exp_f32_e32 v86, v86
	v_exp_f32_e32 v87, v87
	v_mul_f32_e32 v88, 0xbfb8aa3b, v88
	v_mul_f32_e32 v89, 0xbfb8aa3b, v89
	v_fmamk_f32 v82, v82, 0x3b808081, v227
	v_fmamk_f32 v83, v83, 0x3b808081, v227
	v_mul_f32_e32 v84, 0xbfb8aa3b, v84
	v_mul_f32_e32 v85, 0xbfb8aa3b, v85
	v_lshl_or_b32 v127, v127, 8, v130
	v_rndne_f32_e32 v122, v122
	v_rndne_f32_e32 v123, v123
	v_lshl_or_b32 v118, v119, 8, v118
	v_exp_f32_e32 v96, v96
	v_exp_f32_e32 v97, v97
	v_exp_f32_e32 v88, v88
	v_exp_f32_e32 v89, v89
	v_rcp_f32_e32 v82, v82
	v_rcp_f32_e32 v83, v83
	v_exp_f32_e32 v84, v84
	v_exp_f32_e32 v85, v85
	v_mul_f32_e32 v66, 0xbfb8aa3b, v66
	v_mul_f32_e32 v67, 0xbfb8aa3b, v67
	v_or3_b32 v127, v127, v128, v129
	v_cvt_u32_f32_e32 v122, v122
	v_cvt_u32_f32_e32 v123, v123
	v_rndne_f32_e32 v124, v124
	v_rndne_f32_e32 v125, v125
	v_or3_b32 v129, v118, v120, v121
	v_mov_b64_e32 v[118:119], s[0:1]
	v_fmamk_f32 v106, v106, 0x3b808081, v227
	v_fmamk_f32 v107, v107, 0x3b808081, v227
	v_exp_f32_e32 v66, v66
	v_exp_f32_e32 v67, v67
	v_cvt_u32_f32_sdwa v124, v124 dst_sel:WORD_1 dst_unused:UNUSED_PAD src0_sel:DWORD
	v_cvt_u32_f32_sdwa v125, v125 dst_sel:BYTE_3 dst_unused:UNUSED_PAD src0_sel:DWORD
	v_mad_i64_i32 v[120:121], s[40:41], v158, s4, v[118:119]
	v_or3_b32 v110, v114, v115, v116
	v_rndne_f32_e32 v114, v117
	v_rndne_f32_e32 v111, v111
	v_rcp_f32_e32 v106, v106
	v_rcp_f32_e32 v107, v107
	v_fmamk_f32 v108, v108, 0x3b808081, v227
	v_fmamk_f32 v109, v109, 0x3b808081, v227
	v_rndne_f32_e32 v102, v102
	v_rndne_f32_e32 v103, v103
	v_fmamk_f32 v94, v94, 0x3b808081, v227
	v_mul_f32_e32 v90, 0xbfb8aa3b, v90
	v_mul_f32_e32 v91, 0xbfb8aa3b, v91
	v_lshl_add_u64 v[120:121], v[120:121], 0, s[24:25]
	v_cvt_u32_f32_e32 v114, v114
	v_cvt_u32_f32_e32 v111, v111
	v_rndne_f32_e32 v112, v112
	v_rndne_f32_e32 v113, v113
	v_rcp_f32_e32 v108, v108
	v_rcp_f32_e32 v109, v109
	v_cvt_u32_f32_e32 v102, v102
	v_cvt_u32_f32_e32 v103, v103
	v_rndne_f32_e32 v104, v104
	v_rndne_f32_e32 v105, v105
	v_lshl_or_b32 v98, v99, 8, v98
	v_rndne_f32_e32 v99, v100
	v_rndne_f32_e32 v100, v101
	v_rcp_f32_e32 v101, v94
	v_fmamk_f32 v94, v95, 0x3b808081, v227
	v_exp_f32_e32 v90, v90
	v_exp_f32_e32 v91, v91
	v_mul_f32_e32 v92, 0xbfb8aa3b, v92
	v_mul_f32_e32 v93, 0xbfb8aa3b, v93
	v_fmamk_f32 v86, v86, 0x3b808081, v227
	v_fmamk_f32 v87, v87, 0x3b808081, v227
	v_mul_f32_e32 v78, 0xbfb8aa3b, v78
	v_lshl_add_u64 v[120:121], v[120:121], 0, v[144:145]
	s_movk_i32 s3, 0x1000
	v_cvt_u32_f32_sdwa v112, v112 dst_sel:WORD_1 dst_unused:UNUSED_PAD src0_sel:DWORD
	v_cvt_u32_f32_sdwa v113, v113 dst_sel:BYTE_3 dst_unused:UNUSED_PAD src0_sel:DWORD
	v_cvt_u32_f32_sdwa v104, v104 dst_sel:WORD_1 dst_unused:UNUSED_PAD src0_sel:DWORD
	v_cvt_u32_f32_sdwa v105, v105 dst_sel:BYTE_3 dst_unused:UNUSED_PAD src0_sel:DWORD
	v_cvt_u32_f32_sdwa v99, v99 dst_sel:WORD_1 dst_unused:UNUSED_PAD src0_sel:DWORD
	v_cvt_u32_f32_sdwa v100, v100 dst_sel:BYTE_3 dst_unused:UNUSED_PAD src0_sel:DWORD
	v_rcp_f32_e32 v95, v94
	v_fmamk_f32 v96, v96, 0x3b808081, v227
	v_fmamk_f32 v97, v97, 0x3b808081, v227
	v_exp_f32_e32 v92, v92
	v_exp_f32_e32 v93, v93
	v_rcp_f32_e32 v86, v86
	v_rcp_f32_e32 v87, v87
	v_fmamk_f32 v88, v88, 0x3b808081, v227
	v_fmamk_f32 v89, v89, 0x3b808081, v227
	v_rndne_f32_e32 v82, v82
	v_rndne_f32_e32 v83, v83
	v_fmamk_f32 v84, v84, 0x3b808081, v227
	v_fmamk_f32 v85, v85, 0x3b808081, v227
	v_exp_f32_e32 v78, v78
	v_mul_f32_e32 v79, 0xbfb8aa3b, v79
	v_mul_f32_e32 v70, 0xbfb8aa3b, v70
	v_mul_f32_e32 v71, 0xbfb8aa3b, v71
	v_lshl_or_b32 v122, v123, 8, v122
	v_add_co_u32_e32 v120, vcc, s3, v120
	v_rcp_f32_e32 v96, v96
	v_rcp_f32_e32 v97, v97
	v_rcp_f32_e32 v88, v88
	v_rcp_f32_e32 v89, v89
	v_cvt_u32_f32_e32 v82, v82
	v_cvt_u32_f32_e32 v83, v83
	v_rcp_f32_e32 v84, v84
	v_rcp_f32_e32 v85, v85
	v_exp_f32_e32 v79, v79
	v_mul_f32_e32 v80, 0xbfb8aa3b, v80
	v_mul_f32_e32 v81, 0xbfb8aa3b, v81
	v_exp_f32_e32 v70, v70
	v_exp_f32_e32 v71, v71
	v_mul_f32_e32 v72, 0xbfb8aa3b, v72
	v_mul_f32_e32 v73, 0xbfb8aa3b, v73
	v_fmamk_f32 v66, v66, 0x3b808081, v227
	v_fmamk_f32 v67, v67, 0x3b808081, v227
	v_mul_f32_e32 v68, 0xbfb8aa3b, v68
	v_mul_f32_e32 v69, 0xbfb8aa3b, v69
	v_or3_b32 v128, v122, v124, v125
	v_addc_co_u32_e32 v121, vcc, 0, v121, vcc
	v_rndne_f32_e32 v106, v106
	v_rndne_f32_e32 v107, v107
	v_exp_f32_e32 v80, v80
	v_exp_f32_e32 v81, v81
	v_exp_f32_e32 v72, v72
	v_exp_f32_e32 v73, v73
	v_rcp_f32_e32 v66, v66
	v_rcp_f32_e32 v67, v67
	v_exp_f32_e32 v68, v68
	v_exp_f32_e32 v69, v69
	v_mul_f32_e32 v50, 0xbfb8aa3b, v50
	v_mul_f32_e32 v51, 0xbfb8aa3b, v51
	global_store_dwordx4 v[120:121], v[126:129], off offset:512
	v_or_b32_e32 v120, 16, v158
; __device__ __forceinline__ unsigned q8(float x) { return (unsigned)__float2uint_rn(__builtin_amdgcn_rcpf(fmaf(__expf(-x), 1.0f / 255.0f, 1.0f / 255.0f))); }
; __device__ __forceinline__ unsigned q8x4(const f32x4 v) { return q8(v[0]) | (q8(v[1]) << 8) | (q8(v[2]) << 16) | (q8(v[3]) << 24); }
	v_lshl_or_b32 v111, v111, 8, v114
	v_cvt_u32_f32_e32 v106, v106
	v_cvt_u32_f32_e32 v107, v107
	v_rndne_f32_e32 v108, v108
	v_rndne_f32_e32 v109, v109
	v_lshl_or_b32 v102, v103, 8, v102
	v_fmamk_f32 v90, v90, 0x3b808081, v227
	v_fmamk_f32 v91, v91, 0x3b808081, v227
	v_exp_f32_e32 v50, v50
	v_exp_f32_e32 v51, v51
	v_or3_b32 v111, v111, v112, v113
	v_cvt_u32_f32_sdwa v108, v108 dst_sel:WORD_1 dst_unused:UNUSED_PAD src0_sel:DWORD
	v_cvt_u32_f32_sdwa v109, v109 dst_sel:BYTE_3 dst_unused:UNUSED_PAD src0_sel:DWORD
	v_or3_b32 v113, v102, v104, v105
	v_mad_i64_i32 v[102:103], s[40:41], v120, s4, v[118:119]
	v_or3_b32 v94, v98, v99, v100
	v_rndne_f32_e32 v98, v101
	v_rndne_f32_e32 v95, v95
	v_rcp_f32_e32 v90, v90
	v_rcp_f32_e32 v91, v91
	v_fmamk_f32 v92, v92, 0x3b808081, v227
	v_fmamk_f32 v93, v93, 0x3b808081, v227
	v_rndne_f32_e32 v86, v86
	v_rndne_f32_e32 v87, v87
	v_fmamk_f32 v78, v78, 0x3b808081, v227
	v_mul_f32_e32 v74, 0xbfb8aa3b, v74
	v_mul_f32_e32 v75, 0xbfb8aa3b, v75
	v_lshl_add_u64 v[102:103], v[102:103], 0, s[24:25]
	v_cvt_u32_f32_e32 v98, v98
	v_cvt_u32_f32_e32 v95, v95
	v_rndne_f32_e32 v96, v96
	v_rndne_f32_e32 v97, v97
	v_rcp_f32_e32 v92, v92
	v_rcp_f32_e32 v93, v93
	v_cvt_u32_f32_e32 v86, v86
	v_cvt_u32_f32_e32 v87, v87
	v_rndne_f32_e32 v88, v88
	v_rndne_f32_e32 v89, v89
	v_lshl_or_b32 v82, v83, 8, v82
	v_rndne_f32_e32 v83, v84
	v_rndne_f32_e32 v84, v85
	v_rcp_f32_e32 v85, v78
	v_fmamk_f32 v78, v79, 0x3b808081, v227
	v_exp_f32_e32 v74, v74
	v_exp_f32_e32 v75, v75
	v_mul_f32_e32 v76, 0xbfb8aa3b, v76
	v_mul_f32_e32 v77, 0xbfb8aa3b, v77
	v_fmamk_f32 v70, v70, 0x3b808081, v227
	v_fmamk_f32 v71, v71, 0x3b808081, v227
	v_mul_f32_e32 v62, 0xbfb8aa3b, v62
	v_lshl_add_u64 v[102:103], v[102:103], 0, v[144:145]
	v_cvt_u32_f32_sdwa v96, v96 dst_sel:WORD_1 dst_unused:UNUSED_PAD src0_sel:DWORD
	v_cvt_u32_f32_sdwa v97, v97 dst_sel:BYTE_3 dst_unused:UNUSED_PAD src0_sel:DWORD
	v_cvt_u32_f32_sdwa v88, v88 dst_sel:WORD_1 dst_unused:UNUSED_PAD src0_sel:DWORD
	v_cvt_u32_f32_sdwa v89, v89 dst_sel:BYTE_3 dst_unused:UNUSED_PAD src0_sel:DWORD
	v_cvt_u32_f32_sdwa v83, v83 dst_sel:WORD_1 dst_unused:UNUSED_PAD src0_sel:DWORD
	v_cvt_u32_f32_sdwa v84, v84 dst_sel:BYTE_3 dst_unused:UNUSED_PAD src0_sel:DWORD
	v_rcp_f32_e32 v79, v78
	v_fmamk_f32 v80, v80, 0x3b808081, v227
	v_fmamk_f32 v81, v81, 0x3b808081, v227
	v_exp_f32_e32 v76, v76
	v_exp_f32_e32 v77, v77
	v_rcp_f32_e32 v70, v70
	v_rcp_f32_e32 v71, v71
	v_fmamk_f32 v72, v72, 0x3b808081, v227
	v_fmamk_f32 v73, v73, 0x3b808081, v227
	v_rndne_f32_e32 v66, v66
	v_rndne_f32_e32 v67, v67
	v_fmamk_f32 v68, v68, 0x3b808081, v227
	v_fmamk_f32 v69, v69, 0x3b808081, v227
	v_exp_f32_e32 v62, v62
	v_mul_f32_e32 v63, 0xbfb8aa3b, v63
	v_mul_f32_e32 v54, 0xbfb8aa3b, v54
	v_mul_f32_e32 v55, 0xbfb8aa3b, v55
	v_lshl_or_b32 v106, v107, 8, v106
	v_add_co_u32_e32 v102, vcc, s3, v102
	v_rcp_f32_e32 v80, v80
	v_rcp_f32_e32 v81, v81
	v_rcp_f32_e32 v72, v72
	v_rcp_f32_e32 v73, v73
	v_cvt_u32_f32_e32 v66, v66
	v_cvt_u32_f32_e32 v67, v67
	v_rcp_f32_e32 v68, v68
	v_rcp_f32_e32 v69, v69
	v_exp_f32_e32 v63, v63
	v_mul_f32_e32 v64, 0xbfb8aa3b, v64
	v_mul_f32_e32 v65, 0xbfb8aa3b, v65
	v_exp_f32_e32 v54, v54
	v_exp_f32_e32 v55, v55
	v_mul_f32_e32 v56, 0xbfb8aa3b, v56
	v_mul_f32_e32 v57, 0xbfb8aa3b, v57
	v_fmamk_f32 v50, v50, 0x3b808081, v227
	v_fmamk_f32 v51, v51, 0x3b808081, v227
	v_mul_f32_e32 v52, 0xbfb8aa3b, v52
	v_mul_f32_e32 v53, 0xbfb8aa3b, v53
	v_or3_b32 v112, v106, v108, v109
	v_addc_co_u32_e32 v103, vcc, 0, v103, vcc
	v_rndne_f32_e32 v90, v90
	v_rndne_f32_e32 v91, v91
	v_exp_f32_e32 v64, v64
	v_exp_f32_e32 v65, v65
	v_exp_f32_e32 v56, v56
	v_exp_f32_e32 v57, v57
	v_rcp_f32_e32 v50, v50
	v_rcp_f32_e32 v51, v51
	v_exp_f32_e32 v52, v52
	v_exp_f32_e32 v53, v53
	v_mul_f32_e32 v34, 0xbfb8aa3b, v34
	v_mul_f32_e32 v35, 0xbfb8aa3b, v35
	global_store_dwordx4 v[102:103], v[110:113], off offset:512
	v_or_b32_e32 v102, 32, v158
	v_lshl_or_b32 v95, v95, 8, v98
	v_cvt_u32_f32_e32 v90, v90
	v_cvt_u32_f32_e32 v91, v91
	v_rndne_f32_e32 v92, v92
	v_rndne_f32_e32 v93, v93
	v_lshl_or_b32 v86, v87, 8, v86
	v_fmamk_f32 v74, v74, 0x3b808081, v227
	v_fmamk_f32 v75, v75, 0x3b808081, v227
	v_exp_f32_e32 v34, v34
	v_exp_f32_e32 v35, v35
	v_or3_b32 v95, v95, v96, v97
	v_cvt_u32_f32_sdwa v92, v92 dst_sel:WORD_1 dst_unused:UNUSED_PAD src0_sel:DWORD
	v_cvt_u32_f32_sdwa v93, v93 dst_sel:BYTE_3 dst_unused:UNUSED_PAD src0_sel:DWORD
	v_or3_b32 v97, v86, v88, v89
	v_mad_i64_i32 v[86:87], s[40:41], v102, s4, v[118:119]
	v_or3_b32 v78, v82, v83, v84
	v_rndne_f32_e32 v82, v85
	v_rndne_f32_e32 v79, v79
	v_rcp_f32_e32 v74, v74
	v_rcp_f32_e32 v75, v75
	v_fmamk_f32 v76, v76, 0x3b808081, v227
	v_fmamk_f32 v77, v77, 0x3b808081, v227
	v_rndne_f32_e32 v70, v70
	v_rndne_f32_e32 v71, v71
	v_fmamk_f32 v62, v62, 0x3b808081, v227
	v_mul_f32_e32 v58, 0xbfb8aa3b, v58
	v_mul_f32_e32 v59, 0xbfb8aa3b, v59
	v_lshl_add_u64 v[86:87], v[86:87], 0, s[24:25]
	v_cvt_u32_f32_e32 v82, v82
	v_cvt_u32_f32_e32 v79, v79
	v_rndne_f32_e32 v80, v80
	v_rndne_f32_e32 v81, v81
	v_rcp_f32_e32 v76, v76
	v_rcp_f32_e32 v77, v77
	v_cvt_u32_f32_e32 v70, v70
	v_cvt_u32_f32_e32 v71, v71
	v_rndne_f32_e32 v72, v72
	v_rndne_f32_e32 v73, v73
	v_lshl_or_b32 v66, v67, 8, v66
	v_rndne_f32_e32 v67, v68
	v_rndne_f32_e32 v68, v69
	v_rcp_f32_e32 v69, v62
	v_fmamk_f32 v62, v63, 0x3b808081, v227
	v_exp_f32_e32 v58, v58
	v_exp_f32_e32 v59, v59
	v_mul_f32_e32 v60, 0xbfb8aa3b, v60
	v_mul_f32_e32 v61, 0xbfb8aa3b, v61
	v_fmamk_f32 v54, v54, 0x3b808081, v227
	v_fmamk_f32 v55, v55, 0x3b808081, v227
	v_mul_f32_e32 v46, 0xbfb8aa3b, v46
	v_lshl_add_u64 v[86:87], v[86:87], 0, v[144:145]
	v_cvt_u32_f32_sdwa v80, v80 dst_sel:WORD_1 dst_unused:UNUSED_PAD src0_sel:DWORD
; __device__ __forceinline__ unsigned q8(float x) { return (unsigned)__float2uint_rn(__builtin_amdgcn_rcpf(fmaf(__expf(-x), 1.0f / 255.0f, 1.0f / 255.0f))); }
; __device__ __forceinline__ unsigned q8x4(const f32x4 v) { return q8(v[0]) | (q8(v[1]) << 8) | (q8(v[2]) << 16) | (q8(v[3]) << 24); }
	v_cvt_u32_f32_sdwa v81, v81 dst_sel:BYTE_3 dst_unused:UNUSED_PAD src0_sel:DWORD
	v_cvt_u32_f32_sdwa v72, v72 dst_sel:WORD_1 dst_unused:UNUSED_PAD src0_sel:DWORD
	v_cvt_u32_f32_sdwa v73, v73 dst_sel:BYTE_3 dst_unused:UNUSED_PAD src0_sel:DWORD
	v_cvt_u32_f32_sdwa v67, v67 dst_sel:WORD_1 dst_unused:UNUSED_PAD src0_sel:DWORD
	v_cvt_u32_f32_sdwa v68, v68 dst_sel:BYTE_3 dst_unused:UNUSED_PAD src0_sel:DWORD
	v_rcp_f32_e32 v63, v62
	v_fmamk_f32 v64, v64, 0x3b808081, v227
	v_fmamk_f32 v65, v65, 0x3b808081, v227
	v_exp_f32_e32 v60, v60
	v_exp_f32_e32 v61, v61
	v_rcp_f32_e32 v54, v54
	v_rcp_f32_e32 v55, v55
	v_fmamk_f32 v56, v56, 0x3b808081, v227
	v_fmamk_f32 v57, v57, 0x3b808081, v227
	v_rndne_f32_e32 v50, v50
	v_rndne_f32_e32 v51, v51
	v_fmamk_f32 v52, v52, 0x3b808081, v227
	v_fmamk_f32 v53, v53, 0x3b808081, v227
	v_exp_f32_e32 v46, v46
	v_mul_f32_e32 v47, 0xbfb8aa3b, v47
	v_mul_f32_e32 v38, 0xbfb8aa3b, v38
	v_mul_f32_e32 v39, 0xbfb8aa3b, v39
	v_lshl_or_b32 v90, v91, 8, v90
	v_add_co_u32_e32 v86, vcc, s3, v86
	v_rcp_f32_e32 v64, v64
	v_rcp_f32_e32 v65, v65
	v_rcp_f32_e32 v56, v56
	v_rcp_f32_e32 v57, v57
	v_cvt_u32_f32_e32 v50, v50
	v_cvt_u32_f32_e32 v51, v51
	v_rcp_f32_e32 v52, v52
	v_rcp_f32_e32 v53, v53
	v_exp_f32_e32 v47, v47
	v_mul_f32_e32 v48, 0xbfb8aa3b, v48
	v_mul_f32_e32 v49, 0xbfb8aa3b, v49
	v_exp_f32_e32 v38, v38
	v_exp_f32_e32 v39, v39
	v_mul_f32_e32 v40, 0xbfb8aa3b, v40
	v_mul_f32_e32 v41, 0xbfb8aa3b, v41
	v_fmamk_f32 v34, v34, 0x3b808081, v227
	v_fmamk_f32 v35, v35, 0x3b808081, v227
	v_mul_f32_e32 v36, 0xbfb8aa3b, v36
	v_mul_f32_e32 v37, 0xbfb8aa3b, v37
	v_or3_b32 v96, v90, v92, v93
	v_addc_co_u32_e32 v87, vcc, 0, v87, vcc
	v_rndne_f32_e32 v74, v74
	v_rndne_f32_e32 v75, v75
	v_exp_f32_e32 v48, v48
	v_exp_f32_e32 v49, v49
	v_exp_f32_e32 v40, v40
	v_exp_f32_e32 v41, v41
	v_rcp_f32_e32 v34, v34
	v_rcp_f32_e32 v35, v35
	v_exp_f32_e32 v36, v36
	v_exp_f32_e32 v37, v37
	v_mul_f32_e32 v18, 0xbfb8aa3b, v18
	v_mul_f32_e32 v19, 0xbfb8aa3b, v19
	global_store_dwordx4 v[86:87], v[94:97], off offset:512
	v_or_b32_e32 v86, 48, v158
	v_lshl_or_b32 v79, v79, 8, v82
	v_cvt_u32_f32_e32 v74, v74
	v_cvt_u32_f32_e32 v75, v75
	v_rndne_f32_e32 v76, v76
	v_rndne_f32_e32 v77, v77
	v_lshl_or_b32 v70, v71, 8, v70
	v_fmamk_f32 v58, v58, 0x3b808081, v227
	v_fmamk_f32 v59, v59, 0x3b808081, v227
	v_exp_f32_e32 v18, v18
	v_exp_f32_e32 v19, v19
	v_or3_b32 v79, v79, v80, v81
	v_cvt_u32_f32_sdwa v76, v76 dst_sel:WORD_1 dst_unused:UNUSED_PAD src0_sel:DWORD
	v_cvt_u32_f32_sdwa v77, v77 dst_sel:BYTE_3 dst_unused:UNUSED_PAD src0_sel:DWORD
	v_or3_b32 v81, v70, v72, v73
	v_mad_i64_i32 v[70:71], s[40:41], v86, s4, v[118:119]
	v_or3_b32 v62, v66, v67, v68
	v_rndne_f32_e32 v66, v69
	v_rndne_f32_e32 v63, v63
	v_rcp_f32_e32 v58, v58
	v_rcp_f32_e32 v59, v59
	v_fmamk_f32 v60, v60, 0x3b808081, v227
	v_fmamk_f32 v61, v61, 0x3b808081, v227
	v_rndne_f32_e32 v54, v54
	v_rndne_f32_e32 v55, v55
	v_fmamk_f32 v46, v46, 0x3b808081, v227
	v_mul_f32_e32 v42, 0xbfb8aa3b, v42
	v_mul_f32_e32 v43, 0xbfb8aa3b, v43
	v_lshl_add_u64 v[70:71], v[70:71], 0, s[24:25]
	v_cvt_u32_f32_e32 v66, v66
	v_cvt_u32_f32_e32 v63, v63
	v_rndne_f32_e32 v64, v64
	v_rndne_f32_e32 v65, v65
	v_rcp_f32_e32 v60, v60
	v_rcp_f32_e32 v61, v61
	v_cvt_u32_f32_e32 v54, v54
	v_cvt_u32_f32_e32 v55, v55
	v_rndne_f32_e32 v56, v56
	v_rndne_f32_e32 v57, v57
	v_lshl_or_b32 v50, v51, 8, v50
	v_rndne_f32_e32 v51, v52
	v_rndne_f32_e32 v52, v53
	v_rcp_f32_e32 v53, v46
	v_fmamk_f32 v46, v47, 0x3b808081, v227
	v_exp_f32_e32 v42, v42
	v_exp_f32_e32 v43, v43
	v_mul_f32_e32 v44, 0xbfb8aa3b, v44
	v_mul_f32_e32 v45, 0xbfb8aa3b, v45
	v_fmamk_f32 v38, v38, 0x3b808081, v227
	v_fmamk_f32 v39, v39, 0x3b808081, v227
	v_mul_f32_e32 v30, 0xbfb8aa3b, v30
	v_lshl_add_u64 v[70:71], v[70:71], 0, v[144:145]
	v_cvt_u32_f32_sdwa v64, v64 dst_sel:WORD_1 dst_unused:UNUSED_PAD src0_sel:DWORD
	v_cvt_u32_f32_sdwa v65, v65 dst_sel:BYTE_3 dst_unused:UNUSED_PAD src0_sel:DWORD
	v_cvt_u32_f32_sdwa v56, v56 dst_sel:WORD_1 dst_unused:UNUSED_PAD src0_sel:DWORD
	v_cvt_u32_f32_sdwa v57, v57 dst_sel:BYTE_3 dst_unused:UNUSED_PAD src0_sel:DWORD
	v_cvt_u32_f32_sdwa v51, v51 dst_sel:WORD_1 dst_unused:UNUSED_PAD src0_sel:DWORD
	v_cvt_u32_f32_sdwa v52, v52 dst_sel:BYTE_3 dst_unused:UNUSED_PAD src0_sel:DWORD
	v_rcp_f32_e32 v47, v46
	v_fmamk_f32 v48, v48, 0x3b808081, v227
	v_fmamk_f32 v49, v49, 0x3b808081, v227
	v_exp_f32_e32 v44, v44
	v_exp_f32_e32 v45, v45
	v_rcp_f32_e32 v38, v38
	v_rcp_f32_e32 v39, v39
	v_fmamk_f32 v40, v40, 0x3b808081, v227
	v_fmamk_f32 v41, v41, 0x3b808081, v227
	v_rndne_f32_e32 v34, v34
	v_rndne_f32_e32 v35, v35
	v_fmamk_f32 v36, v36, 0x3b808081, v227
	v_fmamk_f32 v37, v37, 0x3b808081, v227
	v_exp_f32_e32 v30, v30
	v_mul_f32_e32 v31, 0xbfb8aa3b, v31
	v_mul_f32_e32 v22, 0xbfb8aa3b, v22
	v_mul_f32_e32 v23, 0xbfb8aa3b, v23
	v_lshl_or_b32 v74, v75, 8, v74
	v_add_co_u32_e32 v70, vcc, s3, v70
	v_rcp_f32_e32 v48, v48
	v_rcp_f32_e32 v49, v49
	v_rcp_f32_e32 v40, v40
	v_rcp_f32_e32 v41, v41
	v_cvt_u32_f32_e32 v34, v34
	v_cvt_u32_f32_e32 v35, v35
	v_rcp_f32_e32 v36, v36
	v_rcp_f32_e32 v37, v37
	v_exp_f32_e32 v31, v31
	v_mul_f32_e32 v32, 0xbfb8aa3b, v32
	v_mul_f32_e32 v33, 0xbfb8aa3b, v33
	v_exp_f32_e32 v22, v22
	v_exp_f32_e32 v23, v23
	v_mul_f32_e32 v24, 0xbfb8aa3b, v24
	v_mul_f32_e32 v25, 0xbfb8aa3b, v25
	v_fmamk_f32 v18, v18, 0x3b808081, v227
	v_fmamk_f32 v19, v19, 0x3b808081, v227
	v_mul_f32_e32 v20, 0xbfb8aa3b, v20
	v_mul_f32_e32 v21, 0xbfb8aa3b, v21
	v_or3_b32 v80, v74, v76, v77
	v_addc_co_u32_e32 v71, vcc, 0, v71, vcc
	v_rndne_f32_e32 v58, v58
	v_rndne_f32_e32 v59, v59
	v_exp_f32_e32 v32, v32
	v_exp_f32_e32 v33, v33
	v_exp_f32_e32 v24, v24
	v_exp_f32_e32 v25, v25
; __device__ __forceinline__ unsigned q8(float x) { return (unsigned)__float2uint_rn(__builtin_amdgcn_rcpf(fmaf(__expf(-x), 1.0f / 255.0f, 1.0f / 255.0f))); }
; __device__ __forceinline__ unsigned q8x4(const f32x4 v) { return q8(v[0]) | (q8(v[1]) << 8) | (q8(v[2]) << 16) | (q8(v[3]) << 24); }
	v_rcp_f32_e32 v18, v18
	v_rcp_f32_e32 v19, v19
	v_exp_f32_e32 v20, v20
	v_exp_f32_e32 v21, v21
	global_store_dwordx4 v[70:71], v[78:81], off offset:512
	v_add_u32_e32 v70, 0x80, v158
	v_lshl_or_b32 v63, v63, 8, v66
	v_cvt_u32_f32_e32 v58, v58
	v_cvt_u32_f32_e32 v59, v59
	v_rndne_f32_e32 v60, v60
	v_rndne_f32_e32 v61, v61
	v_lshl_or_b32 v54, v55, 8, v54
	v_fmamk_f32 v42, v42, 0x3b808081, v227
	v_fmamk_f32 v43, v43, 0x3b808081, v227
	v_or3_b32 v63, v63, v64, v65
	v_cvt_u32_f32_sdwa v60, v60 dst_sel:WORD_1 dst_unused:UNUSED_PAD src0_sel:DWORD
	v_cvt_u32_f32_sdwa v61, v61 dst_sel:BYTE_3 dst_unused:UNUSED_PAD src0_sel:DWORD
	v_or3_b32 v65, v54, v56, v57
	v_mad_i64_i32 v[54:55], s[40:41], v70, s4, v[118:119]
	v_or3_b32 v46, v50, v51, v52
	v_rndne_f32_e32 v50, v53
	v_rndne_f32_e32 v47, v47
	v_rcp_f32_e32 v42, v42
	v_rcp_f32_e32 v43, v43
	v_fmamk_f32 v44, v44, 0x3b808081, v227
	v_fmamk_f32 v45, v45, 0x3b808081, v227
	v_rndne_f32_e32 v38, v38
	v_rndne_f32_e32 v39, v39
	v_fmamk_f32 v30, v30, 0x3b808081, v227
	v_mul_f32_e32 v26, 0xbfb8aa3b, v26
	v_mul_f32_e32 v27, 0xbfb8aa3b, v27
	v_lshl_add_u64 v[54:55], v[54:55], 0, s[24:25]
	v_cvt_u32_f32_e32 v50, v50
	v_cvt_u32_f32_e32 v47, v47
	v_rndne_f32_e32 v48, v48
	v_rndne_f32_e32 v49, v49
	v_rcp_f32_e32 v44, v44
	v_rcp_f32_e32 v45, v45
	v_cvt_u32_f32_e32 v38, v38
	v_cvt_u32_f32_e32 v39, v39
	v_rndne_f32_e32 v40, v40
	v_rndne_f32_e32 v41, v41
	v_lshl_or_b32 v34, v35, 8, v34
	v_rndne_f32_e32 v35, v36
	v_rndne_f32_e32 v36, v37
	v_rcp_f32_e32 v37, v30
	v_fmamk_f32 v30, v31, 0x3b808081, v227
	v_exp_f32_e32 v26, v26
	v_exp_f32_e32 v27, v27
	v_mul_f32_e32 v28, 0xbfb8aa3b, v28
	v_mul_f32_e32 v29, 0xbfb8aa3b, v29
	v_fmamk_f32 v22, v22, 0x3b808081, v227
	v_fmamk_f32 v23, v23, 0x3b808081, v227
	v_mul_f32_e32 v8, 0xbfb8aa3b, v8
	v_lshl_add_u64 v[54:55], v[54:55], 0, v[144:145]
	v_cvt_u32_f32_sdwa v48, v48 dst_sel:WORD_1 dst_unused:UNUSED_PAD src0_sel:DWORD
	v_cvt_u32_f32_sdwa v49, v49 dst_sel:BYTE_3 dst_unused:UNUSED_PAD src0_sel:DWORD
	v_cvt_u32_f32_sdwa v40, v40 dst_sel:WORD_1 dst_unused:UNUSED_PAD src0_sel:DWORD
	v_cvt_u32_f32_sdwa v41, v41 dst_sel:BYTE_3 dst_unused:UNUSED_PAD src0_sel:DWORD
	v_cvt_u32_f32_sdwa v35, v35 dst_sel:WORD_1 dst_unused:UNUSED_PAD src0_sel:DWORD
	v_cvt_u32_f32_sdwa v36, v36 dst_sel:BYTE_3 dst_unused:UNUSED_PAD src0_sel:DWORD
	v_rcp_f32_e32 v31, v30
	v_fmamk_f32 v32, v32, 0x3b808081, v227
	v_fmamk_f32 v33, v33, 0x3b808081, v227
	v_exp_f32_e32 v28, v28
	v_exp_f32_e32 v29, v29
	v_rcp_f32_e32 v22, v22
	v_rcp_f32_e32 v23, v23
	v_fmamk_f32 v24, v24, 0x3b808081, v227
	v_fmamk_f32 v25, v25, 0x3b808081, v227
	v_rndne_f32_e32 v18, v18
	v_rndne_f32_e32 v19, v19
	v_fmamk_f32 v20, v20, 0x3b808081, v227
	v_fmamk_f32 v21, v21, 0x3b808081, v227
	v_exp_f32_e32 v8, v8
	v_mul_f32_e32 v9, 0xbfb8aa3b, v9
	v_mul_f32_e32 v0, 0xbfb8aa3b, v0
	v_mul_f32_e32 v1, 0xbfb8aa3b, v1
	v_lshl_or_b32 v58, v59, 8, v58
	v_add_co_u32_e32 v54, vcc, s3, v54
	v_rcp_f32_e32 v32, v32
	v_rcp_f32_e32 v33, v33
	v_rcp_f32_e32 v24, v24
	v_rcp_f32_e32 v25, v25
	v_cvt_u32_f32_e32 v18, v18
	v_cvt_u32_f32_e32 v19, v19
	v_rcp_f32_e32 v20, v20
	v_rcp_f32_e32 v21, v21
	v_exp_f32_e32 v9, v9
	v_mul_f32_e32 v10, 0xbfb8aa3b, v10
	v_mul_f32_e32 v11, 0xbfb8aa3b, v11
	v_exp_f32_e32 v0, v0
	v_exp_f32_e32 v1, v1
	v_mul_f32_e32 v2, 0xbfb8aa3b, v2
	v_mul_f32_e32 v3, 0xbfb8aa3b, v3
	v_or3_b32 v64, v58, v60, v61
	v_addc_co_u32_e32 v55, vcc, 0, v55, vcc
	v_rndne_f32_e32 v42, v42
	v_rndne_f32_e32 v43, v43
	v_exp_f32_e32 v10, v10
	v_exp_f32_e32 v11, v11
	v_exp_f32_e32 v2, v2
	v_exp_f32_e32 v3, v3
	global_store_dwordx4 v[54:55], v[62:65], off offset:512
	v_add_u32_e32 v54, 0x90, v158
	v_lshl_or_b32 v47, v47, 8, v50
	v_cvt_u32_f32_e32 v42, v42
	v_cvt_u32_f32_e32 v43, v43
	v_rndne_f32_e32 v44, v44
	v_rndne_f32_e32 v45, v45
	v_lshl_or_b32 v38, v39, 8, v38
	v_fmamk_f32 v26, v26, 0x3b808081, v227
	v_fmamk_f32 v27, v27, 0x3b808081, v227
	v_or3_b32 v47, v47, v48, v49
	v_cvt_u32_f32_sdwa v44, v44 dst_sel:WORD_1 dst_unused:UNUSED_PAD src0_sel:DWORD
	v_cvt_u32_f32_sdwa v45, v45 dst_sel:BYTE_3 dst_unused:UNUSED_PAD src0_sel:DWORD
	v_or3_b32 v49, v38, v40, v41
	v_mad_i64_i32 v[38:39], s[40:41], v54, s4, v[118:119]
	v_or3_b32 v30, v34, v35, v36
	v_rndne_f32_e32 v34, v37
	v_rndne_f32_e32 v31, v31
	v_rcp_f32_e32 v26, v26
	v_rcp_f32_e32 v27, v27
	v_fmamk_f32 v28, v28, 0x3b808081, v227
	v_fmamk_f32 v29, v29, 0x3b808081, v227
	v_rndne_f32_e32 v22, v22
; __device__ __forceinline__ unsigned q8(float x) { return (unsigned)__float2uint_rn(__builtin_amdgcn_rcpf(fmaf(__expf(-x), 1.0f / 255.0f, 1.0f / 255.0f))); }
; __device__ __forceinline__ unsigned q8x4(const f32x4 v) { return q8(v[0]) | (q8(v[1]) << 8) | (q8(v[2]) << 16) | (q8(v[3]) << 24); }
	v_rndne_f32_e32 v23, v23
	v_fmamk_f32 v8, v8, 0x3b808081, v227
	v_mul_f32_e32 v4, 0xbfb8aa3b, v4
	v_mul_f32_e32 v5, 0xbfb8aa3b, v5
	v_lshl_add_u64 v[38:39], v[38:39], 0, s[24:25]
	v_cvt_u32_f32_e32 v34, v34
	v_cvt_u32_f32_e32 v31, v31
	v_rndne_f32_e32 v32, v32
	v_rndne_f32_e32 v33, v33
	v_rcp_f32_e32 v28, v28
	v_rcp_f32_e32 v29, v29
	v_cvt_u32_f32_e32 v22, v22
	v_cvt_u32_f32_e32 v23, v23
	v_rndne_f32_e32 v24, v24
	v_rndne_f32_e32 v25, v25
	v_lshl_or_b32 v18, v19, 8, v18
	v_rndne_f32_e32 v19, v20
	v_rndne_f32_e32 v20, v21
	v_rcp_f32_e32 v21, v8
	v_fmamk_f32 v8, v9, 0x3b808081, v227
	v_exp_f32_e32 v4, v4
	v_exp_f32_e32 v5, v5
	v_mul_f32_e32 v6, 0xbfb8aa3b, v6
	v_mul_f32_e32 v7, 0xbfb8aa3b, v7
	v_fmamk_f32 v0, v0, 0x3b808081, v227
	v_fmamk_f32 v1, v1, 0x3b808081, v227
	v_lshl_add_u64 v[38:39], v[38:39], 0, v[144:145]
	v_cvt_u32_f32_sdwa v32, v32 dst_sel:WORD_1 dst_unused:UNUSED_PAD src0_sel:DWORD
	v_cvt_u32_f32_sdwa v33, v33 dst_sel:BYTE_3 dst_unused:UNUSED_PAD src0_sel:DWORD
	v_cvt_u32_f32_sdwa v24, v24 dst_sel:WORD_1 dst_unused:UNUSED_PAD src0_sel:DWORD
	v_cvt_u32_f32_sdwa v25, v25 dst_sel:BYTE_3 dst_unused:UNUSED_PAD src0_sel:DWORD
	v_cvt_u32_f32_sdwa v19, v19 dst_sel:WORD_1 dst_unused:UNUSED_PAD src0_sel:DWORD
	v_cvt_u32_f32_sdwa v20, v20 dst_sel:BYTE_3 dst_unused:UNUSED_PAD src0_sel:DWORD
	v_rcp_f32_e32 v9, v8
	v_fmamk_f32 v10, v10, 0x3b808081, v227
	v_fmamk_f32 v11, v11, 0x3b808081, v227
	v_exp_f32_e32 v6, v6
	v_exp_f32_e32 v7, v7
	v_rcp_f32_e32 v0, v0
	v_rcp_f32_e32 v1, v1
	v_fmamk_f32 v2, v2, 0x3b808081, v227
	v_fmamk_f32 v3, v3, 0x3b808081, v227
	v_lshl_or_b32 v42, v43, 8, v42
	v_add_co_u32_e32 v38, vcc, s3, v38
	v_rcp_f32_e32 v10, v10
	v_rcp_f32_e32 v11, v11
	v_rcp_f32_e32 v2, v2
	v_rcp_f32_e32 v3, v3
	v_or3_b32 v48, v42, v44, v45
	v_addc_co_u32_e32 v39, vcc, 0, v39, vcc
	v_rndne_f32_e32 v26, v26
	v_rndne_f32_e32 v27, v27
	global_store_dwordx4 v[38:39], v[46:49], off offset:512
	v_add_u32_e32 v38, 0xa0, v158
	v_lshl_or_b32 v31, v31, 8, v34
	v_cvt_u32_f32_e32 v26, v26
	v_cvt_u32_f32_e32 v27, v27
	v_rndne_f32_e32 v28, v28
	v_rndne_f32_e32 v29, v29
	v_lshl_or_b32 v22, v23, 8, v22
	v_fmamk_f32 v4, v4, 0x3b808081, v227
	v_fmamk_f32 v5, v5, 0x3b808081, v227
	v_or3_b32 v31, v31, v32, v33
	v_cvt_u32_f32_sdwa v28, v28 dst_sel:WORD_1 dst_unused:UNUSED_PAD src0_sel:DWORD
	v_cvt_u32_f32_sdwa v29, v29 dst_sel:BYTE_3 dst_unused:UNUSED_PAD src0_sel:DWORD
	v_or3_b32 v33, v22, v24, v25
	v_mad_i64_i32 v[22:23], s[40:41], v38, s4, v[118:119]
	v_or3_b32 v8, v18, v19, v20
	v_rndne_f32_e32 v18, v21
	v_rndne_f32_e32 v9, v9
	v_rcp_f32_e32 v4, v4
	v_rcp_f32_e32 v5, v5
	v_fmamk_f32 v6, v6, 0x3b808081, v227
	v_fmamk_f32 v7, v7, 0x3b808081, v227
	v_rndne_f32_e32 v0, v0
	v_rndne_f32_e32 v1, v1
	v_lshl_add_u64 v[22:23], v[22:23], 0, s[24:25]
	v_cvt_u32_f32_e32 v18, v18
	v_cvt_u32_f32_e32 v9, v9
	v_rndne_f32_e32 v10, v10
	v_rndne_f32_e32 v11, v11
	v_rcp_f32_e32 v6, v6
	v_rcp_f32_e32 v7, v7
	v_cvt_u32_f32_e32 v0, v0
	v_cvt_u32_f32_e32 v1, v1
	v_rndne_f32_e32 v2, v2
	v_rndne_f32_e32 v3, v3
	v_lshl_add_u64 v[22:23], v[22:23], 0, v[144:145]
	v_cvt_u32_f32_sdwa v10, v10 dst_sel:WORD_1 dst_unused:UNUSED_PAD src0_sel:DWORD
	v_cvt_u32_f32_sdwa v11, v11 dst_sel:BYTE_3 dst_unused:UNUSED_PAD src0_sel:DWORD
	v_cvt_u32_f32_sdwa v2, v2 dst_sel:WORD_1 dst_unused:UNUSED_PAD src0_sel:DWORD
	v_cvt_u32_f32_sdwa v3, v3 dst_sel:BYTE_3 dst_unused:UNUSED_PAD src0_sel:DWORD
	v_lshl_or_b32 v26, v27, 8, v26
	v_add_co_u32_e32 v22, vcc, s3, v22
	v_or3_b32 v32, v26, v28, v29
	s_nop 0
	v_addc_co_u32_e32 v23, vcc, 0, v23, vcc
	v_rndne_f32_e32 v4, v4
	v_rndne_f32_e32 v5, v5
	global_store_dwordx4 v[22:23], v[30:33], off offset:512
	v_add_u32_e32 v22, 0xb0, v158
	v_lshl_or_b32 v9, v9, 8, v18
	v_cvt_u32_f32_e32 v4, v4
	v_cvt_u32_f32_e32 v5, v5
	v_rndne_f32_e32 v6, v6
	v_rndne_f32_e32 v7, v7
	v_lshl_or_b32 v0, v1, 8, v0
	v_or3_b32 v9, v9, v10, v11
	v_cvt_u32_f32_sdwa v6, v6 dst_sel:WORD_1 dst_unused:UNUSED_PAD src0_sel:DWORD
	v_cvt_u32_f32_sdwa v7, v7 dst_sel:BYTE_3 dst_unused:UNUSED_PAD src0_sel:DWORD
	v_or3_b32 v11, v0, v2, v3
	v_mad_i64_i32 v[0:1], s[40:41], v22, s4, v[118:119]
	v_lshl_add_u64 v[0:1], v[0:1], 0, s[24:25]
	v_lshl_add_u64 v[0:1], v[0:1], 0, v[144:145]
	v_lshl_or_b32 v4, v5, 8, v4
	v_add_co_u32_e32 v0, vcc, 0x1000, v0
	v_or3_b32 v10, v4, v6, v7
	s_nop 0
	v_addc_co_u32_e32 v1, vcc, 0, v1, vcc
	global_store_dwordx4 v[0:1], v[8:11], off offset:512
	s_branch .LBB0_1220
